# LayerNorm phases: gamma and beta copied once per workgroup into LDS and read with ds_read (were 32 global reloads per row each behind vmcnt(0), which also drained the next-row prefetch and the stores)
# speedup vs baseline: 1.0028x; 1.0028x over previous
.LBB0_789:
	s_cmp_lt_i32 s72, 8
	s_cselect_b64 s[2:3], -1, 0
	s_and_b64 s[4:5], s[2:3], s[6:7]
	s_andn2_b64 vcc, exec, s[4:5]
	s_cbranch_vccnz .LBB0_796
	s_load_dwordx2 s[98:99], s[0:1], 0xb0
	s_load_dwordx2 s[100:101], s[0:1], 0xb8
	v_lshlrev_b32_e32 v2, 4, v0
	v_add_u32_e32 v3, 0x2000, v2
	v_and_b32_e32 v251, 63, v0
	v_lshlrev_b32_e32 v251, 5, v251
	s_waitcnt lgkmcnt(0)
	global_load_dwordx4 v[4:7], v2, s[98:99]
	global_load_dwordx4 v[8:11], v3, s[98:99]
	global_load_dwordx4 v[12:15], v2, s[100:101]
	global_load_dwordx4 v[16:19], v3, s[100:101]
	s_waitcnt vmcnt(0)
	ds_write_b128 v2, v[4:7]
	ds_write_b128 v3, v[8:11]
	ds_write_b128 v2, v[12:15] offset:16384
	ds_write_b128 v3, v[16:19] offset:16384
	s_waitcnt lgkmcnt(0)
	s_barrier
	s_waitcnt vmcnt(0)
	v_lshl_or_b32 v66, s76, 3, v1
	s_movk_i32 s2, 0x4000
	v_cmp_gt_i32_e32 vcc, s2, v66
	s_and_saveexec_b64 s[12:13], vcc
	s_cbranch_execz .LBB0_795
	v_ashrrev_i32_e32 v67, 31, v66
	v_and_b32_e32 v38, 63, v0
	v_lshlrev_b64 v[68:69], 13, v[66:67]
	v_mov_b32_e32 v70, 0
	v_lshl_add_u64 v[2:3], s[90:91], 0, v[68:69]
	v_lshlrev_b32_e32 v34, 4, v38
	v_mov_b32_e32 v35, v70
	v_lshl_add_u64 v[18:19], v[2:3], 0, v[34:35]
	s_movk_i32 s3, 0x1000
	v_add_co_u32_e32 v36, vcc, s3, v18
	global_load_dwordx4 v[2:5], v[18:19], off
	global_load_dwordx4 v[6:9], v[18:19], off offset:1024
	global_load_dwordx4 v[10:13], v[18:19], off offset:2048
	global_load_dwordx4 v[14:17], v[18:19], off offset:3072
	v_addc_co_u32_e32 v37, vcc, 0, v19, vcc
	global_load_dwordx4 v[18:21], v[36:37], off
	global_load_dwordx4 v[22:25], v[36:37], off offset:1024
	global_load_dwordx4 v[26:29], v[36:37], off offset:2048
	global_load_dwordx4 v[30:33], v[36:37], off offset:3072
	v_lshl_add_u64 v[72:73], s[90:91], 0, v[34:35]
	v_mbcnt_lo_u32_b32 v35, -1, 0
	v_mbcnt_hi_u32_b32 v35, -1, v35
	v_and_b32_e32 v36, 64, v35
	v_add_u32_e32 v36, 64, v36
	v_xor_b32_e32 v37, 32, v35
	v_cmp_lt_i32_e32 vcc, v37, v36
	s_load_dwordx4 s[8:11], s[0:1], 0xb0
	v_mov_b32_e32 v39, v70
	v_cndmask_b32_e32 v37, v35, v37, vcc
	v_lshlrev_b32_e32 v104, 2, v37
	v_xor_b32_e32 v37, 16, v35
	v_cmp_lt_i32_e32 vcc, v37, v36
	s_lshl_b32 s14, s80, 3
	s_ashr_i32 s15, s14, 31
	v_cndmask_b32_e32 v37, v35, v37, vcc
	v_lshlrev_b32_e32 v105, 2, v37
	v_xor_b32_e32 v37, 8, v35
	v_cmp_lt_i32_e32 vcc, v37, v36
	v_or_b32_e32 v68, v68, v34
	s_lshl_b64 s[16:17], s[14:15], 13
	v_cndmask_b32_e32 v37, v35, v37, vcc
	v_lshlrev_b32_e32 v106, 2, v37
	v_xor_b32_e32 v37, 4, v35
	v_cmp_lt_i32_e32 vcc, v37, v36
	s_mov_b64 s[18:19], 0
	s_mov_b32 s20, 0xb9800000
	v_cndmask_b32_e32 v37, v35, v37, vcc
	v_lshlrev_b32_e32 v107, 2, v37
	v_xor_b32_e32 v37, 2, v35
	v_cmp_lt_i32_e32 vcc, v37, v36
	s_mov_b32 s21, 0x800000
	s_mov_b32 s22, 0xb510000
	v_cndmask_b32_e32 v37, v35, v37, vcc
	v_lshlrev_b32_e32 v108, 2, v37
	v_xor_b32_e32 v37, 1, v35
	v_cmp_lt_i32_e32 vcc, v37, v36
	v_lshlrev_b32_e32 v36, 5, v38
	s_mov_b32 s23, 0xb511000
	v_cndmask_b32_e32 v35, v35, v37, vcc
	v_cmp_eq_u32_e32 vcc, 0, v38
	v_or_b32_e32 v38, 0x1000, v36
	s_waitcnt lgkmcnt(0)
	v_lshl_add_u64 v[78:79], s[8:9], 0, v[38:39]
	v_lshl_add_u64 v[80:81], s[10:11], 0, v[38:39]
	v_or_b32_e32 v38, 0x1800, v36
	v_mov_b32_e32 v37, v70
	v_lshl_add_u64 v[82:83], s[8:9], 0, v[38:39]
	v_lshl_add_u64 v[84:85], s[10:11], 0, v[38:39]
	v_or_b32_e32 v38, 0x2000, v36
	v_lshlrev_b32_e32 v109, 2, v35
	v_lshl_add_u64 v[74:75], s[8:9], 0, v[36:37]
	v_lshl_add_u64 v[76:77], s[10:11], 0, v[36:37]
	v_lshl_add_u64 v[86:87], s[8:9], 0, v[38:39]
	v_lshl_add_u64 v[88:89], s[10:11], 0, v[38:39]
	v_or_b32_e32 v38, 0x2800, v36
	v_or_b32_e32 v36, 0x3000, v36
	v_mov_b32_e32 v35, 0x3800
	v_lshl_add_u64 v[94:95], s[8:9], 0, v[36:37]
	v_lshl_add_u64 v[96:97], s[10:11], 0, v[36:37]
	v_lshl_or_b32 v36, v0, 5, v35
	v_lshl_add_u64 v[98:99], s[8:9], 0, v[36:37]
	v_lshl_add_u64 v[100:101], s[10:11], 0, v[36:37]
	v_mov_b64_e32 v[36:37], 0x65c10000
	v_lshl_add_u64 v[90:91], s[8:9], 0, v[38:39]
	v_lshl_add_u64 v[92:93], s[10:11], 0, v[38:39]
	v_lshl_add_u64 v[102:103], v[66:67], 3, v[36:37]
	s_lshl_b64 s[10:11], s[14:15], 3
	s_movk_i32 s15, 0x3fff
	v_mov_b32_e32 v67, 0x3727c5ac
	s_branch .LBB0_793
.LBB0_792:
	s_or_b64 exec, exec, s[8:9]
	ds_read_b128 v[146:149], v251 offset:16
	ds_read_b128 v[150:153], v251 offset:0
	ds_read_b128 v[154:157], v251 offset:16384
	ds_read_b128 v[158:161], v251 offset:16400
	v_lshl_add_u64 v[162:163], s[74:75], 0, v[68:69]
	v_mul_f32_e32 v36, v140, v37
	v_mul_f32_e32 v140, v144, v37
	v_mul_f32_e32 v138, v138, v37
	v_mul_f32_e32 v139, v139, v37
	v_add_co_u32_e64 v40, s[8:9], s23, v162
	v_mul_f32_e32 v143, v143, v37
	v_mul_f32_e32 v142, v142, v37
	v_mul_f32_e32 v137, v137, v37
	v_mul_f32_e32 v141, v141, v37
	v_addc_co_u32_e64 v41, s[8:9], 0, v163, s[8:9]
	v_mul_f32_e32 v131, v131, v37
	v_mul_f32_e32 v135, v135, v37
	v_mul_f32_e32 v130, v130, v37
	v_mul_f32_e32 v134, v134, v37
	v_mul_f32_e32 v129, v129, v37
	v_mul_f32_e32 v133, v133, v37
	v_mul_f32_e32 v123, v123, v37
	v_mul_f32_e32 v127, v127, v37
	v_mul_f32_e32 v122, v122, v37
	v_mul_f32_e32 v126, v126, v37
	v_mul_f32_e32 v121, v121, v37
	v_mul_f32_e32 v125, v125, v37
	v_mul_f32_e32 v115, v115, v37
	v_mul_f32_e32 v119, v119, v37
	v_mul_f32_e32 v114, v114, v37
	v_mul_f32_e32 v118, v118, v37
	v_mul_f32_e32 v113, v113, v37
	v_mul_f32_e32 v117, v117, v37
	v_mul_f32_e32 v64, v64, v37
	v_mul_f32_e32 v63, v63, v37
	v_mul_f32_e32 v111, v111, v37
	v_mul_f32_e32 v110, v110, v37
	v_mul_f32_e32 v62, v62, v37
	v_mul_f32_e32 v71, v71, v37
	v_mul_f32_e32 v56, v56, v37
	v_mul_f32_e32 v55, v55, v37
	v_mul_f32_e32 v60, v60, v37
	v_mul_f32_e32 v59, v59, v37
	v_mul_f32_e32 v54, v54, v37
	v_mul_f32_e32 v58, v58, v37
	v_mul_f32_e32 v48, v48, v37
	v_mul_f32_e32 v47, v47, v37
	v_mul_f32_e32 v52, v52, v37
	v_mul_f32_e32 v51, v51, v37
	v_mul_f32_e32 v46, v46, v37
	v_mul_f32_e32 v50, v50, v37
	s_and_b64 s[6:7], exec, s[6:7]
	v_mul_f32_e32 v38, v38, v37
	v_mul_f32_e32 v44, v44, v37
	v_mul_f32_e32 v39, v39, v37
	v_mul_f32_e32 v43, v43, v37
	v_mul_f32_e32 v34, v34, v37
	v_mul_f32_e32 v42, v42, v37
	v_mul_f32_e32 v35, v35, v37
	v_lshl_add_u64 v[102:103], v[102:103], 0, s[10:11]
	s_or_b64 s[18:19], s[6:7], s[18:19]
	v_lshl_add_u64 v[68:69], v[68:69], 0, s[16:17]
	s_waitcnt lgkmcnt(1)
	v_fma_f32 v138, v138, v151, v155
	s_waitcnt lgkmcnt(0)
	v_fma_f32 v140, v140, v146, v158
	v_fma_f32 v139, v139, v152, v156
	v_fma_f32 v36, v36, v150, v154
	v_fma_f32 v143, v143, v147, v159
	v_fma_f32 v142, v142, v148, v160
	v_fmac_f32_e32 v157, v137, v153
	v_fmac_f32_e32 v161, v141, v149
	v_cvt_pk_bf16_f32 v138, v36, v138
	v_cvt_pk_bf16_f32 v139, v139, v157
	v_cvt_pk_bf16_f32 v140, v140, v143
	v_cvt_pk_bf16_f32 v141, v142, v161
	global_store_dwordx4 v[40:41], v[138:141], off offset:-4096
	ds_read_b128 v[138:141], v251 offset:2064
	s_nop 0
	ds_read_b128 v[142:145], v251 offset:2048
	ds_read_b128 v[146:149], v251 offset:18432
	ds_read_b128 v[150:153], v251 offset:18448
	v_mul_f32_e32 v36, v132, v37
	v_mul_f32_e32 v132, v136, v37
	v_add_co_u32_e64 v154, s[8:9], s22, v162
	s_waitcnt lgkmcnt(1)
	v_fma_f32 v131, v131, v143, v147
	v_addc_co_u32_e64 v155, s[8:9], 0, v163, s[8:9]
	s_waitcnt lgkmcnt(0)
	v_fma_f32 v132, v132, v138, v150
	v_fma_f32 v36, v36, v142, v146
	v_fma_f32 v135, v135, v139, v151
	v_fma_f32 v136, v130, v144, v148
	v_fma_f32 v134, v134, v140, v152
	v_fmac_f32_e32 v149, v129, v145
	v_fmac_f32_e32 v153, v133, v141
	v_cvt_pk_bf16_f32 v130, v36, v131
	v_cvt_pk_bf16_f32 v131, v136, v149
	v_cvt_pk_bf16_f32 v132, v132, v135
	v_cvt_pk_bf16_f32 v133, v134, v153
	global_store_dwordx4 v[154:155], v[130:133], off offset:1024
	ds_read_b128 v[130:133], v251 offset:4112
	s_nop 0
	ds_read_b128 v[134:137], v251 offset:4096
	ds_read_b128 v[138:141], v251 offset:20480
	ds_read_b128 v[142:145], v251 offset:20496
	v_mul_f32_e32 v36, v124, v37
	v_mul_f32_e32 v124, v128, v37
	s_waitcnt lgkmcnt(1)
	v_fma_f32 v123, v123, v135, v139
	s_waitcnt lgkmcnt(0)
	v_fma_f32 v124, v124, v130, v142
	v_fma_f32 v36, v36, v134, v138
	v_fma_f32 v127, v127, v131, v143
	v_fma_f32 v128, v122, v136, v140
	v_fma_f32 v126, v126, v132, v144
	v_fmac_f32_e32 v141, v121, v137
	v_fmac_f32_e32 v145, v125, v133
	v_cvt_pk_bf16_f32 v122, v36, v123
	v_cvt_pk_bf16_f32 v123, v128, v141
	v_cvt_pk_bf16_f32 v124, v124, v127
	v_cvt_pk_bf16_f32 v125, v126, v145
	global_store_dwordx4 v[154:155], v[122:125], off offset:2048
	ds_read_b128 v[122:125], v251 offset:6160
	s_nop 0
	ds_read_b128 v[126:129], v251 offset:6144
	ds_read_b128 v[130:133], v251 offset:22528
	ds_read_b128 v[134:137], v251 offset:22544
	v_mul_f32_e32 v36, v116, v37
	v_mul_f32_e32 v116, v120, v37
	s_waitcnt lgkmcnt(1)
	v_fma_f32 v115, v115, v127, v131
	s_waitcnt lgkmcnt(0)
	v_fma_f32 v116, v116, v122, v134
	v_fma_f32 v36, v36, v126, v130
	v_fma_f32 v119, v119, v123, v135
	v_fma_f32 v120, v114, v128, v132
	v_fma_f32 v118, v118, v124, v136
	v_fmac_f32_e32 v133, v113, v129
	v_fmac_f32_e32 v137, v117, v125
	v_cvt_pk_bf16_f32 v114, v36, v115
	v_cvt_pk_bf16_f32 v115, v120, v133
	v_cvt_pk_bf16_f32 v116, v116, v119
	v_cvt_pk_bf16_f32 v117, v118, v137
	global_store_dwordx4 v[154:155], v[114:117], off offset:3072
	ds_read_b128 v[114:117], v251 offset:8208
	s_nop 0
	ds_read_b128 v[118:121], v251 offset:8192
	ds_read_b128 v[122:125], v251 offset:24576
	ds_read_b128 v[126:129], v251 offset:24592
	v_mul_f32_e32 v36, v65, v37
	v_mul_f32_e32 v65, v112, v37
	s_waitcnt lgkmcnt(1)
	v_fma_f32 v64, v64, v119, v123
	s_waitcnt lgkmcnt(0)
	v_fma_f32 v65, v65, v114, v126
	v_fma_f32 v63, v63, v120, v124
	v_fma_f32 v36, v36, v118, v122
	v_fma_f32 v111, v111, v115, v127
	v_fma_f32 v110, v110, v116, v128
	v_fmac_f32_e32 v125, v62, v121
	v_fmac_f32_e32 v129, v71, v117
	v_cvt_pk_bf16_f32 v62, v36, v64
	v_cvt_pk_bf16_f32 v63, v63, v125
	v_cvt_pk_bf16_f32 v64, v65, v111
	v_cvt_pk_bf16_f32 v65, v110, v129
	global_store_dwordx4 v[40:41], v[62:65], off
	ds_read_b128 v[62:65], v251 offset:10256
	s_nop 0
	ds_read_b128 v[110:113], v251 offset:10240
	ds_read_b128 v[114:117], v251 offset:26624
	ds_read_b128 v[118:121], v251 offset:26640
	v_mul_f32_e32 v36, v57, v37
	v_mul_f32_e32 v57, v61, v37
	s_waitcnt lgkmcnt(1)
	v_fma_f32 v56, v56, v111, v115
	s_waitcnt lgkmcnt(0)
	v_fma_f32 v57, v57, v62, v118
	v_fma_f32 v55, v55, v112, v116
	v_fma_f32 v36, v36, v110, v114
	v_fma_f32 v60, v60, v63, v119
	v_fma_f32 v59, v59, v64, v120
	v_fmac_f32_e32 v117, v54, v113
	v_fmac_f32_e32 v121, v58, v65
	v_cvt_pk_bf16_f32 v54, v36, v56
	v_cvt_pk_bf16_f32 v55, v55, v117
	v_cvt_pk_bf16_f32 v56, v57, v60
	v_cvt_pk_bf16_f32 v57, v59, v121
	global_store_dwordx4 v[40:41], v[54:57], off offset:1024
	ds_read_b128 v[54:57], v251 offset:12304
	s_nop 0
	ds_read_b128 v[58:61], v251 offset:12288
	ds_read_b128 v[62:65], v251 offset:28672
	ds_read_b128 v[110:113], v251 offset:28688
	v_mul_f32_e32 v36, v49, v37
	v_mul_f32_e32 v49, v53, v37
	s_waitcnt lgkmcnt(1)
	v_fma_f32 v48, v48, v59, v63
	s_waitcnt lgkmcnt(0)
	v_fma_f32 v49, v49, v54, v110
	v_fma_f32 v47, v47, v60, v64
	v_fma_f32 v36, v36, v58, v62
	v_fma_f32 v52, v52, v55, v111
	v_fma_f32 v51, v51, v56, v112
	v_fmac_f32_e32 v65, v46, v61
	v_fmac_f32_e32 v113, v50, v57
	v_cvt_pk_bf16_f32 v46, v36, v48
	v_cvt_pk_bf16_f32 v47, v47, v65
	v_cvt_pk_bf16_f32 v48, v49, v52
	v_cvt_pk_bf16_f32 v49, v51, v113
	global_store_dwordx4 v[40:41], v[46:49], off offset:2048
	ds_read_b128 v[46:49], v251 offset:14352
	s_nop 0
	ds_read_b128 v[50:53], v251 offset:14336
	ds_read_b128 v[54:57], v251 offset:30720
	ds_read_b128 v[58:61], v251 offset:30736
	v_mul_f32_e32 v36, v45, v37
	s_waitcnt lgkmcnt(1)
	v_fma_f32 v36, v36, v50, v54
	s_waitcnt lgkmcnt(0)
	v_fma_f32 v37, v38, v46, v58
	v_fma_f32 v38, v44, v51, v55
	v_fma_f32 v39, v39, v47, v59
	v_fma_f32 v43, v43, v52, v56
	v_fma_f32 v44, v34, v48, v60
	v_fmac_f32_e32 v57, v42, v53
	v_fmac_f32_e32 v61, v35, v49
	v_cvt_pk_bf16_f32 v34, v36, v38
	v_cvt_pk_bf16_f32 v35, v43, v57
	v_cvt_pk_bf16_f32 v36, v37, v39
	v_cvt_pk_bf16_f32 v37, v44, v61
	global_store_dwordx4 v[40:41], v[34:37], off offset:3072
	s_andn2_b64 exec, exec, s[18:19]
	s_cbranch_execz .LBB0_795

.LBB0_1016:
	s_load_dwordx2 s[2:3], s[0:1], 0x310
	s_waitcnt lgkmcnt(0)
	s_cmp_lt_i32 s2, 11
	s_cselect_b64 s[2:3], -1, 0
	s_and_b64 s[4:5], s[2:3], s[6:7]
	s_andn2_b64 vcc, exec, s[4:5]
	s_cbranch_vccnz .LBB0_1023
	s_load_dwordx2 s[98:99], s[0:1], 0xc0
	s_load_dwordx2 s[100:101], s[0:1], 0xc8
	v_lshlrev_b32_e32 v2, 4, v0
	v_add_u32_e32 v3, 0x2000, v2
	v_and_b32_e32 v251, 63, v0
	v_lshlrev_b32_e32 v251, 5, v251
	s_waitcnt lgkmcnt(0)
	global_load_dwordx4 v[4:7], v2, s[98:99]
	global_load_dwordx4 v[8:11], v3, s[98:99]
	global_load_dwordx4 v[12:15], v2, s[100:101]
	global_load_dwordx4 v[16:19], v3, s[100:101]
	s_waitcnt vmcnt(0)
	ds_write_b128 v2, v[4:7]
	ds_write_b128 v3, v[8:11]
	ds_write_b128 v2, v[12:15] offset:16384
	ds_write_b128 v3, v[16:19] offset:16384
	s_waitcnt lgkmcnt(0)
	s_barrier
	s_waitcnt vmcnt(0)
	v_lshl_or_b32 v66, s76, 3, v1
	s_movk_i32 s2, 0x4000
	v_cmp_gt_i32_e32 vcc, s2, v66
	s_and_saveexec_b64 s[12:13], vcc
	s_cbranch_execz .LBB0_1022
	v_ashrrev_i32_e32 v67, 31, v66
	v_and_b32_e32 v38, 63, v0
	v_lshlrev_b64 v[68:69], 13, v[66:67]
	v_mov_b32_e32 v70, 0
	v_lshl_add_u64 v[2:3], s[94:95], 0, v[68:69]
	v_lshlrev_b32_e32 v34, 4, v38
	v_mov_b32_e32 v35, v70
	v_lshl_add_u64 v[18:19], v[2:3], 0, v[34:35]
	s_movk_i32 s3, 0x1000
	v_add_co_u32_e32 v36, vcc, s3, v18
	global_load_dwordx4 v[2:5], v[18:19], off
	global_load_dwordx4 v[6:9], v[18:19], off offset:1024
	global_load_dwordx4 v[10:13], v[18:19], off offset:2048
	global_load_dwordx4 v[14:17], v[18:19], off offset:3072
	v_addc_co_u32_e32 v37, vcc, 0, v19, vcc
	global_load_dwordx4 v[18:21], v[36:37], off
	global_load_dwordx4 v[22:25], v[36:37], off offset:1024
	global_load_dwordx4 v[26:29], v[36:37], off offset:2048
	global_load_dwordx4 v[30:33], v[36:37], off offset:3072
	v_lshl_add_u64 v[72:73], s[94:95], 0, v[34:35]
	v_mbcnt_lo_u32_b32 v35, -1, 0
	v_mbcnt_hi_u32_b32 v35, -1, v35
	v_and_b32_e32 v36, 64, v35
	v_add_u32_e32 v36, 64, v36
	v_xor_b32_e32 v37, 32, v35
	v_cmp_lt_i32_e32 vcc, v37, v36
	s_load_dwordx4 s[8:11], s[0:1], 0xc0
	v_mov_b32_e32 v39, v70
	v_cndmask_b32_e32 v37, v35, v37, vcc
	v_lshlrev_b32_e32 v104, 2, v37
	v_xor_b32_e32 v37, 16, v35
	v_cmp_lt_i32_e32 vcc, v37, v36
	s_lshl_b32 s14, s80, 3
	s_ashr_i32 s15, s14, 31
	v_cndmask_b32_e32 v37, v35, v37, vcc
	v_lshlrev_b32_e32 v105, 2, v37
	v_xor_b32_e32 v37, 8, v35
	v_cmp_lt_i32_e32 vcc, v37, v36
	v_or_b32_e32 v68, v68, v34
	s_lshl_b64 s[16:17], s[14:15], 13
	v_cndmask_b32_e32 v37, v35, v37, vcc
	v_lshlrev_b32_e32 v106, 2, v37
	v_xor_b32_e32 v37, 4, v35
	v_cmp_lt_i32_e32 vcc, v37, v36
	s_mov_b64 s[18:19], 0
	s_mov_b32 s20, 0xb9800000
	v_cndmask_b32_e32 v37, v35, v37, vcc
	v_lshlrev_b32_e32 v107, 2, v37
	v_xor_b32_e32 v37, 2, v35
	v_cmp_lt_i32_e32 vcc, v37, v36
	s_mov_b32 s21, 0x800000
	s_mov_b32 s22, 0xb510000
	v_cndmask_b32_e32 v37, v35, v37, vcc
	v_lshlrev_b32_e32 v108, 2, v37
	v_xor_b32_e32 v37, 1, v35
	v_cmp_lt_i32_e32 vcc, v37, v36
	v_lshlrev_b32_e32 v36, 5, v38
	s_mov_b32 s23, 0xb511000
	v_cndmask_b32_e32 v35, v35, v37, vcc
	v_cmp_eq_u32_e32 vcc, 0, v38
	v_or_b32_e32 v38, 0x1000, v36
	s_waitcnt lgkmcnt(0)
	v_lshl_add_u64 v[78:79], s[8:9], 0, v[38:39]
	v_lshl_add_u64 v[80:81], s[10:11], 0, v[38:39]
	v_or_b32_e32 v38, 0x1800, v36
	v_mov_b32_e32 v37, v70
	v_lshl_add_u64 v[82:83], s[8:9], 0, v[38:39]
	v_lshl_add_u64 v[84:85], s[10:11], 0, v[38:39]
	v_or_b32_e32 v38, 0x2000, v36
	v_lshlrev_b32_e32 v109, 2, v35
	v_lshl_add_u64 v[74:75], s[8:9], 0, v[36:37]
	v_lshl_add_u64 v[76:77], s[10:11], 0, v[36:37]
	v_lshl_add_u64 v[86:87], s[8:9], 0, v[38:39]
	v_lshl_add_u64 v[88:89], s[10:11], 0, v[38:39]
	v_or_b32_e32 v38, 0x2800, v36
	v_or_b32_e32 v36, 0x3000, v36
	v_mov_b32_e32 v35, 0x3800
	v_lshl_add_u64 v[94:95], s[8:9], 0, v[36:37]
	v_lshl_add_u64 v[96:97], s[10:11], 0, v[36:37]
	v_lshl_or_b32 v36, v0, 5, v35
	v_lshl_add_u64 v[98:99], s[8:9], 0, v[36:37]
	v_lshl_add_u64 v[100:101], s[10:11], 0, v[36:37]
	v_mov_b64_e32 v[36:37], 0x65c10000
	v_lshl_add_u64 v[90:91], s[8:9], 0, v[38:39]
	v_lshl_add_u64 v[92:93], s[10:11], 0, v[38:39]
	v_lshl_add_u64 v[102:103], v[66:67], 3, v[36:37]
	s_lshl_b64 s[10:11], s[14:15], 3
	s_movk_i32 s15, 0x3fff
	v_mov_b32_e32 v67, 0x3727c5ac
	s_branch .LBB0_1020

.LBB0_2203:
	s_cmp_lt_i32 s56, 20
	s_cselect_b64 s[2:3], -1, 0
	s_and_b64 s[4:5], s[2:3], s[6:7]
	s_andn2_b64 vcc, exec, s[4:5]
	s_cbranch_vccnz .LBB0_2210
	s_load_dwordx2 s[98:99], s[0:1], 0xb0
	s_load_dwordx2 s[100:101], s[0:1], 0xb8
	v_lshlrev_b32_e32 v2, 4, v0
	v_add_u32_e32 v3, 0x2000, v2
	v_and_b32_e32 v251, 63, v0
	v_lshlrev_b32_e32 v251, 5, v251
	s_waitcnt lgkmcnt(0)
	s_add_u32 s98, s98, 0x4000
	s_addc_u32 s99, s99, 0
	s_add_u32 s100, s100, 0x4000
	s_addc_u32 s101, s101, 0
	global_load_dwordx4 v[4:7], v2, s[98:99]
	global_load_dwordx4 v[8:11], v3, s[98:99]
	global_load_dwordx4 v[12:15], v2, s[100:101]
	global_load_dwordx4 v[16:19], v3, s[100:101]
	s_waitcnt vmcnt(0)
	ds_write_b128 v2, v[4:7]
	ds_write_b128 v3, v[8:11]
	ds_write_b128 v2, v[12:15] offset:16384
	ds_write_b128 v3, v[16:19] offset:16384
	s_waitcnt lgkmcnt(0)
	s_barrier
	s_waitcnt vmcnt(0)
	v_lshl_or_b32 v66, s76, 3, v1
	s_movk_i32 s2, 0x4000
	v_cmp_gt_i32_e32 vcc, s2, v66
	s_and_saveexec_b64 s[10:11], vcc
	s_cbranch_execz .LBB0_2209
	v_ashrrev_i32_e32 v67, 31, v66
	v_and_b32_e32 v38, 63, v0
	v_lshlrev_b64 v[68:69], 13, v[66:67]
	v_mov_b32_e32 v70, 0
	v_lshl_add_u64 v[2:3], s[90:91], 0, v[68:69]
	v_lshlrev_b32_e32 v34, 4, v38
	v_mov_b32_e32 v35, v70
	v_lshl_add_u64 v[18:19], v[2:3], 0, v[34:35]
	s_movk_i32 s3, 0x1000
	v_add_co_u32_e32 v36, vcc, s3, v18
	global_load_dwordx4 v[2:5], v[18:19], off
	global_load_dwordx4 v[6:9], v[18:19], off offset:1024
	global_load_dwordx4 v[10:13], v[18:19], off offset:2048
	global_load_dwordx4 v[14:17], v[18:19], off offset:3072
	v_addc_co_u32_e32 v37, vcc, 0, v19, vcc
	global_load_dwordx4 v[18:21], v[36:37], off
	global_load_dwordx4 v[22:25], v[36:37], off offset:1024
	global_load_dwordx4 v[26:29], v[36:37], off offset:2048
	global_load_dwordx4 v[30:33], v[36:37], off offset:3072
	v_lshl_add_u64 v[72:73], s[90:91], 0, v[34:35]
	v_mbcnt_lo_u32_b32 v35, -1, 0
	v_mbcnt_hi_u32_b32 v35, -1, v35
	v_and_b32_e32 v36, 64, v35
	v_add_u32_e32 v36, 64, v36
	v_xor_b32_e32 v37, 32, v35
	v_cmp_lt_i32_e32 vcc, v37, v36
	s_load_dwordx4 s[16:19], s[0:1], 0xb0
	s_lshl_b32 s12, s80, 3
	v_cndmask_b32_e32 v37, v35, v37, vcc
	v_lshlrev_b32_e32 v108, 2, v37
	v_xor_b32_e32 v37, 16, v35
	v_cmp_lt_i32_e32 vcc, v37, v36
	s_waitcnt lgkmcnt(0)
	s_add_u32 s6, s18, 0x4000
	s_addc_u32 s7, s19, 0
	v_cndmask_b32_e32 v37, v35, v37, vcc
	v_lshlrev_b32_e32 v109, 2, v37
	v_xor_b32_e32 v37, 8, v35
	v_cmp_lt_i32_e32 vcc, v37, v36
	s_add_u32 s8, s16, 0x4000
	s_addc_u32 s9, s17, 0
	v_cndmask_b32_e32 v37, v35, v37, vcc
	v_lshlrev_b32_e32 v110, 2, v37
	v_xor_b32_e32 v37, 4, v35
	v_cmp_lt_i32_e32 vcc, v37, v36
	v_mov_b32_e32 v39, v70
	s_ashr_i32 s13, s12, 31
	v_cndmask_b32_e32 v37, v35, v37, vcc
	v_lshlrev_b32_e32 v111, 2, v37
	v_xor_b32_e32 v37, 2, v35
	v_cmp_lt_i32_e32 vcc, v37, v36
	s_lshl_b64 s[14:15], s[12:13], 3
	v_or_b32_e32 v68, v68, v34
	v_cndmask_b32_e32 v37, v35, v37, vcc
	v_lshlrev_b32_e32 v112, 2, v37
	v_xor_b32_e32 v37, 1, v35
	v_cmp_lt_i32_e32 vcc, v37, v36
	v_lshlrev_b32_e32 v36, 5, v38
	s_lshl_b64 s[16:17], s[12:13], 13
	v_cndmask_b32_e32 v35, v35, v37, vcc
	v_cmp_eq_u32_e32 vcc, 0, v38
	v_or_b32_e32 v38, 0x800, v36
	v_lshl_add_u64 v[78:79], s[8:9], 0, v[38:39]
	v_lshl_add_u64 v[80:81], s[6:7], 0, v[38:39]
	v_or_b32_e32 v38, 0x1000, v36
	v_lshl_add_u64 v[82:83], s[8:9], 0, v[38:39]
	v_lshl_add_u64 v[84:85], s[6:7], 0, v[38:39]
	v_or_b32_e32 v38, 0x1800, v36
	v_mov_b32_e32 v37, v70
	v_lshl_add_u64 v[86:87], s[8:9], 0, v[38:39]
	v_lshl_add_u64 v[88:89], s[6:7], 0, v[38:39]
	v_or_b32_e32 v38, 0x2000, v36
	v_lshlrev_b32_e32 v113, 2, v35
	v_lshl_add_u64 v[74:75], s[8:9], 0, v[36:37]
	v_lshl_add_u64 v[76:77], s[6:7], 0, v[36:37]
	v_lshl_add_u64 v[90:91], s[8:9], 0, v[38:39]
	v_lshl_add_u64 v[92:93], s[6:7], 0, v[38:39]
	v_or_b32_e32 v38, 0x2800, v36
	v_or_b32_e32 v36, 0x3000, v36
	v_mov_b32_e32 v35, 0x3800
	v_lshl_add_u64 v[98:99], s[8:9], 0, v[36:37]
	v_lshl_add_u64 v[100:101], s[6:7], 0, v[36:37]
	v_lshl_or_b32 v36, v0, 5, v35
	v_lshl_add_u64 v[102:103], s[8:9], 0, v[36:37]
	v_lshl_add_u64 v[104:105], s[6:7], 0, v[36:37]
	v_mov_b64_e32 v[36:37], 0x65c10000
	v_lshl_add_u64 v[94:95], s[8:9], 0, v[38:39]
	v_lshl_add_u64 v[96:97], s[6:7], 0, v[38:39]
	v_lshl_add_u64 v[106:107], v[66:67], 3, v[36:37]
	s_mov_b64 s[18:19], 0
	s_movk_i32 s13, 0x3fff
	s_mov_b32 s20, 0xb9800000
	v_mov_b32_e32 v67, 0x3727c5ac
	s_mov_b32 s21, 0x800000
	s_mov_b32 s22, 0xb510000
	s_mov_b32 s23, 0xb511000
	s_branch .LBB0_2207
.LBB0_2206:
	s_or_b64 exec, exec, s[8:9]
	ds_read_b128 v[150:153], v251 offset:16
	ds_read_b128 v[154:157], v251 offset:0
	ds_read_b128 v[158:161], v251 offset:16384
	ds_read_b128 v[162:165], v251 offset:16400
	v_lshl_add_u64 v[166:167], s[74:75], 0, v[68:69]
	v_mul_f32_e32 v36, v144, v37
	v_mul_f32_e32 v144, v148, v37
	v_mul_f32_e32 v142, v142, v37
	v_mul_f32_e32 v143, v143, v37
	v_add_co_u32_e64 v40, s[8:9], s23, v166
	v_mul_f32_e32 v147, v147, v37
	v_mul_f32_e32 v146, v146, v37
	v_mul_f32_e32 v141, v141, v37
	v_mul_f32_e32 v145, v145, v37
	v_addc_co_u32_e64 v41, s[8:9], 0, v167, s[8:9]
	v_mul_f32_e32 v135, v135, v37
	v_mul_f32_e32 v139, v139, v37
	v_mul_f32_e32 v134, v134, v37
	v_mul_f32_e32 v138, v138, v37
	v_mul_f32_e32 v133, v133, v37
	v_mul_f32_e32 v137, v137, v37
	v_mul_f32_e32 v127, v127, v37
	v_mul_f32_e32 v131, v131, v37
	v_mul_f32_e32 v126, v126, v37
	v_mul_f32_e32 v130, v130, v37
	v_mul_f32_e32 v125, v125, v37
	v_mul_f32_e32 v129, v129, v37
	v_mul_f32_e32 v119, v119, v37
	v_mul_f32_e32 v123, v123, v37
	v_mul_f32_e32 v118, v118, v37
	v_mul_f32_e32 v122, v122, v37
	v_mul_f32_e32 v117, v117, v37
	v_mul_f32_e32 v121, v121, v37
	v_mul_f32_e32 v64, v64, v37
	v_mul_f32_e32 v63, v63, v37
	v_mul_f32_e32 v115, v115, v37
	v_mul_f32_e32 v114, v114, v37
	v_mul_f32_e32 v62, v62, v37
	v_mul_f32_e32 v71, v71, v37
	v_mul_f32_e32 v56, v56, v37
	v_mul_f32_e32 v55, v55, v37
	v_mul_f32_e32 v60, v60, v37
	v_mul_f32_e32 v59, v59, v37
	v_mul_f32_e32 v54, v54, v37
	v_mul_f32_e32 v58, v58, v37
	v_mul_f32_e32 v48, v48, v37
	v_mul_f32_e32 v47, v47, v37
	v_mul_f32_e32 v52, v52, v37
	v_mul_f32_e32 v51, v51, v37
	v_mul_f32_e32 v46, v46, v37
	v_mul_f32_e32 v50, v50, v37
	s_and_b64 s[6:7], exec, s[6:7]
	v_mul_f32_e32 v38, v38, v37
	v_mul_f32_e32 v44, v44, v37
	v_mul_f32_e32 v39, v39, v37
	v_mul_f32_e32 v43, v43, v37
	v_mul_f32_e32 v34, v34, v37
	v_mul_f32_e32 v42, v42, v37
	v_mul_f32_e32 v35, v35, v37
	v_lshl_add_u64 v[106:107], v[106:107], 0, s[14:15]
	s_or_b64 s[18:19], s[6:7], s[18:19]
	v_lshl_add_u64 v[68:69], v[68:69], 0, s[16:17]
	s_waitcnt lgkmcnt(1)
	v_fma_f32 v142, v142, v155, v159
	s_waitcnt lgkmcnt(0)
	v_fma_f32 v144, v144, v150, v162
	v_fma_f32 v143, v143, v156, v160
	v_fma_f32 v36, v36, v154, v158
	v_fma_f32 v147, v147, v151, v163
	v_fma_f32 v146, v146, v152, v164
	v_fmac_f32_e32 v161, v141, v157
	v_fmac_f32_e32 v165, v145, v153
	v_cvt_pk_bf16_f32 v142, v36, v142
	v_cvt_pk_bf16_f32 v143, v143, v161
	v_cvt_pk_bf16_f32 v144, v144, v147
	v_cvt_pk_bf16_f32 v145, v146, v165
	global_store_dwordx4 v[40:41], v[142:145], off offset:-4096
	ds_read_b128 v[142:145], v251 offset:2064
	s_nop 0
	ds_read_b128 v[146:149], v251 offset:2048
	ds_read_b128 v[150:153], v251 offset:18432
	ds_read_b128 v[154:157], v251 offset:18448
	v_mul_f32_e32 v36, v136, v37
	v_mul_f32_e32 v136, v140, v37
	v_add_co_u32_e64 v158, s[8:9], s22, v166
	s_waitcnt lgkmcnt(1)
	v_fma_f32 v135, v135, v147, v151
	v_addc_co_u32_e64 v159, s[8:9], 0, v167, s[8:9]
	s_waitcnt lgkmcnt(0)
	v_fma_f32 v136, v136, v142, v154
	v_fma_f32 v36, v36, v146, v150
	v_fma_f32 v139, v139, v143, v155
	v_fma_f32 v140, v134, v148, v152
	v_fma_f32 v138, v138, v144, v156
	v_fmac_f32_e32 v153, v133, v149
	v_fmac_f32_e32 v157, v137, v145
	v_cvt_pk_bf16_f32 v134, v36, v135
	v_cvt_pk_bf16_f32 v135, v140, v153
	v_cvt_pk_bf16_f32 v136, v136, v139
	v_cvt_pk_bf16_f32 v137, v138, v157
	global_store_dwordx4 v[158:159], v[134:137], off offset:1024
	ds_read_b128 v[134:137], v251 offset:4112
	s_nop 0
	ds_read_b128 v[138:141], v251 offset:4096
	ds_read_b128 v[142:145], v251 offset:20480
	ds_read_b128 v[146:149], v251 offset:20496
	v_mul_f32_e32 v36, v128, v37
	v_mul_f32_e32 v128, v132, v37
	s_waitcnt lgkmcnt(1)
	v_fma_f32 v127, v127, v139, v143
	s_waitcnt lgkmcnt(0)
	v_fma_f32 v128, v128, v134, v146
	v_fma_f32 v36, v36, v138, v142
	v_fma_f32 v131, v131, v135, v147
	v_fma_f32 v132, v126, v140, v144
	v_fma_f32 v130, v130, v136, v148
	v_fmac_f32_e32 v145, v125, v141
	v_fmac_f32_e32 v149, v129, v137
	v_cvt_pk_bf16_f32 v126, v36, v127
	v_cvt_pk_bf16_f32 v127, v132, v145
	v_cvt_pk_bf16_f32 v128, v128, v131
	v_cvt_pk_bf16_f32 v129, v130, v149
	global_store_dwordx4 v[158:159], v[126:129], off offset:2048
	ds_read_b128 v[126:129], v251 offset:6160
	s_nop 0
	ds_read_b128 v[130:133], v251 offset:6144
	ds_read_b128 v[134:137], v251 offset:22528
	ds_read_b128 v[138:141], v251 offset:22544
	v_mul_f32_e32 v36, v120, v37
	v_mul_f32_e32 v120, v124, v37
	s_waitcnt lgkmcnt(1)
	v_fma_f32 v119, v119, v131, v135
	s_waitcnt lgkmcnt(0)
	v_fma_f32 v120, v120, v126, v138
	v_fma_f32 v36, v36, v130, v134
	v_fma_f32 v123, v123, v127, v139
	v_fma_f32 v124, v118, v132, v136
	v_fma_f32 v122, v122, v128, v140
	v_fmac_f32_e32 v137, v117, v133
	v_fmac_f32_e32 v141, v121, v129
	v_cvt_pk_bf16_f32 v118, v36, v119
	v_cvt_pk_bf16_f32 v119, v124, v137
	v_cvt_pk_bf16_f32 v120, v120, v123
	v_cvt_pk_bf16_f32 v121, v122, v141
	global_store_dwordx4 v[158:159], v[118:121], off offset:3072
	ds_read_b128 v[118:121], v251 offset:8208
	s_nop 0
	ds_read_b128 v[122:125], v251 offset:8192
	ds_read_b128 v[126:129], v251 offset:24576
	ds_read_b128 v[130:133], v251 offset:24592
	v_mul_f32_e32 v36, v65, v37
	v_mul_f32_e32 v65, v116, v37
	s_waitcnt lgkmcnt(1)
	v_fma_f32 v64, v64, v123, v127
	s_waitcnt lgkmcnt(0)
	v_fma_f32 v65, v65, v118, v130
	v_fma_f32 v63, v63, v124, v128
	v_fma_f32 v36, v36, v122, v126
	v_fma_f32 v115, v115, v119, v131
	v_fma_f32 v114, v114, v120, v132
	v_fmac_f32_e32 v129, v62, v125
	v_fmac_f32_e32 v133, v71, v121
	v_cvt_pk_bf16_f32 v62, v36, v64
	v_cvt_pk_bf16_f32 v63, v63, v129
	v_cvt_pk_bf16_f32 v64, v65, v115
	v_cvt_pk_bf16_f32 v65, v114, v133
	global_store_dwordx4 v[40:41], v[62:65], off
	ds_read_b128 v[62:65], v251 offset:10256
	s_nop 0
	ds_read_b128 v[114:117], v251 offset:10240
	ds_read_b128 v[118:121], v251 offset:26624
	ds_read_b128 v[122:125], v251 offset:26640
	v_mul_f32_e32 v36, v57, v37
	v_mul_f32_e32 v57, v61, v37
	s_waitcnt lgkmcnt(1)
	v_fma_f32 v56, v56, v115, v119
	s_waitcnt lgkmcnt(0)
	v_fma_f32 v57, v57, v62, v122
	v_fma_f32 v55, v55, v116, v120
	v_fma_f32 v36, v36, v114, v118
	v_fma_f32 v60, v60, v63, v123
	v_fma_f32 v59, v59, v64, v124
	v_fmac_f32_e32 v121, v54, v117
	v_fmac_f32_e32 v125, v58, v65
	v_cvt_pk_bf16_f32 v54, v36, v56
	v_cvt_pk_bf16_f32 v55, v55, v121
	v_cvt_pk_bf16_f32 v56, v57, v60
	v_cvt_pk_bf16_f32 v57, v59, v125
	global_store_dwordx4 v[40:41], v[54:57], off offset:1024
	ds_read_b128 v[54:57], v251 offset:12304
	s_nop 0
	ds_read_b128 v[58:61], v251 offset:12288
	ds_read_b128 v[62:65], v251 offset:28672
	ds_read_b128 v[114:117], v251 offset:28688
	v_mul_f32_e32 v36, v49, v37
	v_mul_f32_e32 v49, v53, v37
	s_waitcnt lgkmcnt(1)
	v_fma_f32 v48, v48, v59, v63
	s_waitcnt lgkmcnt(0)
	v_fma_f32 v49, v49, v54, v114
	v_fma_f32 v47, v47, v60, v64
	v_fma_f32 v36, v36, v58, v62
	v_fma_f32 v52, v52, v55, v115
	v_fma_f32 v51, v51, v56, v116
	v_fmac_f32_e32 v65, v46, v61
	v_fmac_f32_e32 v117, v50, v57
	v_cvt_pk_bf16_f32 v46, v36, v48
	v_cvt_pk_bf16_f32 v47, v47, v65
	v_cvt_pk_bf16_f32 v48, v49, v52
	v_cvt_pk_bf16_f32 v49, v51, v117
	global_store_dwordx4 v[40:41], v[46:49], off offset:2048
	ds_read_b128 v[46:49], v251 offset:14352
	s_nop 0
	ds_read_b128 v[50:53], v251 offset:14336
	ds_read_b128 v[54:57], v251 offset:30720
	ds_read_b128 v[58:61], v251 offset:30736
	v_mul_f32_e32 v36, v45, v37
	s_waitcnt lgkmcnt(1)
	v_fma_f32 v36, v36, v50, v54
	s_waitcnt lgkmcnt(0)
	v_fma_f32 v37, v38, v46, v58
	v_fma_f32 v38, v44, v51, v55
	v_fma_f32 v39, v39, v47, v59
	v_fma_f32 v43, v43, v52, v56
	v_fma_f32 v44, v34, v48, v60
	v_fmac_f32_e32 v57, v42, v53
	v_fmac_f32_e32 v61, v35, v49
	v_cvt_pk_bf16_f32 v34, v36, v38
	v_cvt_pk_bf16_f32 v35, v43, v57
	v_cvt_pk_bf16_f32 v36, v37, v39
	v_cvt_pk_bf16_f32 v37, v44, v61
	global_store_dwordx4 v[40:41], v[34:37], off offset:3072
	s_andn2_b64 exec, exec, s[18:19]
	s_cbranch_execz .LBB0_2209

.LBB0_2430:
	s_cmp_lt_i32 s56, 23
	s_cselect_b64 s[2:3], -1, 0
	s_and_b64 s[6:7], s[2:3], s[6:7]
	s_andn2_b64 vcc, exec, s[6:7]
	s_cbranch_vccnz .LBB0_2437
	s_load_dwordx2 s[98:99], s[0:1], 0xc0
	s_load_dwordx2 s[100:101], s[0:1], 0xc8
	v_lshlrev_b32_e32 v2, 4, v0
	v_add_u32_e32 v3, 0x2000, v2
	v_and_b32_e32 v251, 63, v0
	v_lshlrev_b32_e32 v251, 5, v251
	s_waitcnt lgkmcnt(0)
	s_add_u32 s98, s98, 0x4000
	s_addc_u32 s99, s99, 0
	s_add_u32 s100, s100, 0x4000
	s_addc_u32 s101, s101, 0
	global_load_dwordx4 v[4:7], v2, s[98:99]
	global_load_dwordx4 v[8:11], v3, s[98:99]
	global_load_dwordx4 v[12:15], v2, s[100:101]
	global_load_dwordx4 v[16:19], v3, s[100:101]
	s_waitcnt vmcnt(0)
	ds_write_b128 v2, v[4:7]
	ds_write_b128 v3, v[8:11]
	ds_write_b128 v2, v[12:15] offset:16384
	ds_write_b128 v3, v[16:19] offset:16384
	s_waitcnt lgkmcnt(0)
	s_barrier
	v_lshl_or_b32 v34, s76, 3, v1
	s_movk_i32 s14, 0x4000
	v_cmp_gt_i32_e32 vcc, s14, v34
	s_and_saveexec_b64 s[2:3], vcc
	s_cbranch_execz .LBB0_2436
	v_ashrrev_i32_e32 v35, 31, v34
	v_lshlrev_b32_e32 v1, 3, v0
	v_lshlrev_b64 v[2:3], 13, v[34:35]
	v_and_b32_e32 v1, 0x1f8, v1
	v_mov_b32_e32 v36, 0
	v_lshl_add_u64 v[2:3], s[4:5], 0, v[2:3]
	v_lshlrev_b32_e32 v38, 1, v1
	v_mov_b32_e32 v39, v36
	v_lshl_add_u64 v[18:19], v[2:3], 0, v[38:39]
	s_movk_i32 s15, 0x1000
	v_add_co_u32_e32 v40, vcc, s15, v18
	global_load_dwordx4 v[2:5], v[18:19], off
	global_load_dwordx4 v[6:9], v[18:19], off offset:1024
	global_load_dwordx4 v[10:13], v[18:19], off offset:2048
	global_load_dwordx4 v[14:17], v[18:19], off offset:3072
	v_addc_co_u32_e32 v41, vcc, 0, v19, vcc
	global_load_dwordx4 v[18:21], v[40:41], off
	global_load_dwordx4 v[22:25], v[40:41], off offset:1024
	global_load_dwordx4 v[26:29], v[40:41], off offset:2048
	global_load_dwordx4 v[30:33], v[40:41], off offset:3072
	v_mbcnt_lo_u32_b32 v37, -1, 0
	v_mbcnt_hi_u32_b32 v37, -1, v37
	v_and_b32_e32 v40, 64, v37
	v_add_u32_e32 v40, 64, v40
	v_xor_b32_e32 v41, 32, v37
	v_cmp_lt_i32_e32 vcc, v41, v40
	s_load_dwordx4 s[16:19], s[0:1], 0xc0
	s_lshl_b32 s8, s80, 3
	v_cndmask_b32_e32 v41, v37, v41, vcc
	v_lshlrev_b32_e32 v105, 2, v41
	v_xor_b32_e32 v41, 16, v37
	v_cmp_lt_i32_e32 vcc, v41, v40
	s_waitcnt lgkmcnt(0)
	s_add_u32 s0, s18, 0x4000
	s_addc_u32 s1, s19, 0
	v_cndmask_b32_e32 v41, v37, v41, vcc
	v_lshlrev_b32_e32 v138, 2, v41
	v_xor_b32_e32 v41, 8, v37
	v_cmp_lt_i32_e32 vcc, v41, v40
	s_add_u32 s12, s16, 0x4000
	v_readlane_b32 s18, v250, 2
	v_cndmask_b32_e32 v41, v37, v41, vcc
	v_lshlrev_b32_e32 v139, 2, v41
	v_xor_b32_e32 v41, 4, v37
	v_cmp_lt_i32_e32 vcc, v41, v40
	s_addc_u32 s13, s17, 0
	v_readlane_b32 s19, v250, 3
	v_cndmask_b32_e32 v41, v37, v41, vcc
	v_lshlrev_b32_e32 v140, 2, v41
	v_xor_b32_e32 v41, 2, v37
	v_cmp_lt_i32_e32 vcc, v41, v40
	v_lshlrev_b32_e32 v64, 2, v1
	v_mov_b32_e32 v1, 0x3800
	v_cndmask_b32_e32 v41, v37, v41, vcc
	v_lshlrev_b32_e32 v141, 2, v41
	v_xor_b32_e32 v41, 1, v37
	v_cmp_lt_i32_e32 vcc, v41, v40
	s_cmp_lg_u64 s[18:19], 0
	s_waitcnt vmcnt(0)
	v_lshl_or_b32 v70, v0, 5, v1
	v_lshlrev_b64 v[72:73], 14, v[34:35]
	v_and_b32_e32 v0, 63, v0
	v_cndmask_b32_e32 v37, v37, v41, vcc
	s_cselect_b64 s[10:11], -1, 0
	v_mov_b32_e32 v65, v36
	v_or_b32_e32 v46, 0x800, v64
	v_mov_b32_e32 v47, v36
	v_or_b32_e32 v50, 0x1000, v64
	v_mov_b32_e32 v51, v36
	v_or_b32_e32 v54, 0x1800, v64
	v_mov_b32_e32 v55, v36
	v_or_b32_e32 v58, 0x2000, v64
	v_mov_b32_e32 v59, v36
	v_or_b32_e32 v62, 0x2800, v64
	v_mov_b32_e32 v63, v36
	v_or_b32_e32 v66, 0x3000, v64
	v_mov_b32_e32 v67, v36
	v_mov_b32_e32 v71, v36
	v_lshl_or_b32 v72, v0, 5, v72
	s_ashr_i32 s9, s8, 31
	v_lshl_add_u64 v[38:39], s[4:5], 0, v[38:39]
	v_lshlrev_b32_e32 v142, 2, v37
	s_mov_b64 s[4:5], 0
	v_lshl_add_u64 v[40:41], s[12:13], 0, v[64:65]
	v_lshl_add_u64 v[42:43], s[0:1], 0, v[64:65]
	v_lshl_add_u64 v[44:45], s[12:13], 0, v[46:47]
	v_lshl_add_u64 v[46:47], s[0:1], 0, v[46:47]
	v_lshl_add_u64 v[48:49], s[12:13], 0, v[50:51]
	v_lshl_add_u64 v[50:51], s[0:1], 0, v[50:51]
	v_lshl_add_u64 v[52:53], s[12:13], 0, v[54:55]
	v_lshl_add_u64 v[54:55], s[0:1], 0, v[54:55]
	s_movk_i32 s16, 0x2000
	v_lshl_add_u64 v[56:57], s[12:13], 0, v[58:59]
	v_lshl_add_u64 v[58:59], s[0:1], 0, v[58:59]
	v_lshl_add_u64 v[60:61], s[12:13], 0, v[62:63]
	v_lshl_add_u64 v[62:63], s[0:1], 0, v[62:63]
	s_movk_i32 s17, 0x3000
	v_lshl_add_u64 v[64:65], s[12:13], 0, v[66:67]
	v_lshl_add_u64 v[66:67], s[0:1], 0, v[66:67]
	v_lshl_add_u64 v[68:69], s[12:13], 0, v[70:71]
	v_lshl_add_u64 v[70:71], s[0:1], 0, v[70:71]
	v_lshl_add_u64 v[0:1], s[18:19], 0, v[72:73]
	s_lshl_b64 s[12:13], s[8:9], 14
	s_movk_i32 s9, 0x3fff
	v_mov_b32_e32 v35, 0x3727c5ac
	s_mov_b32 s18, 0x800000
	s_branch .LBB0_2434

.LBB0_2434:
	s_waitcnt vmcnt(7)
	v_cvt_f32_f16_sdwa v73, v2 dst_sel:DWORD dst_unused:UNUSED_PAD src0_sel:WORD_1
	v_cvt_f32_f16_e32 v72, v2
	v_cvt_f32_f16_sdwa v77, v4 dst_sel:DWORD dst_unused:UNUSED_PAD src0_sel:WORD_1
	v_cvt_f32_f16_e32 v76, v4
	v_cvt_f32_f16_sdwa v75, v3 dst_sel:DWORD dst_unused:UNUSED_PAD src0_sel:WORD_1
	v_cvt_f32_f16_e32 v74, v3
	v_cvt_f32_f16_sdwa v79, v5 dst_sel:DWORD dst_unused:UNUSED_PAD src0_sel:WORD_1
	v_cvt_f32_f16_e32 v78, v5
	v_mov_b32_e32 v2, v72
	v_mov_b32_e32 v3, v76
	v_mov_b32_e32 v4, v73
	v_mov_b32_e32 v5, v77
	v_pk_add_f32 v[2:3], v[2:3], v[4:5]
	v_mov_b32_e32 v4, v74
	v_mov_b32_e32 v5, v78
	v_mov_b32_e32 v80, v75
	v_mov_b32_e32 v81, v79
	v_pk_add_f32 v[4:5], v[4:5], v[80:81]
	s_waitcnt vmcnt(6)
	v_cvt_f32_f16_e32 v80, v6
	v_cvt_f32_f16_e32 v82, v7
	v_cvt_f32_f16_sdwa v81, v6 dst_sel:DWORD dst_unused:UNUSED_PAD src0_sel:WORD_1
	v_cvt_f32_f16_sdwa v83, v7 dst_sel:DWORD dst_unused:UNUSED_PAD src0_sel:WORD_1
	v_cvt_f32_f16_e32 v84, v8
	v_cvt_f32_f16_e32 v86, v9
	v_cvt_f32_f16_sdwa v85, v8 dst_sel:DWORD dst_unused:UNUSED_PAD src0_sel:WORD_1
	v_cvt_f32_f16_sdwa v87, v9 dst_sel:DWORD dst_unused:UNUSED_PAD src0_sel:WORD_1
	s_waitcnt vmcnt(5)
	v_cvt_f32_f16_sdwa v93, v12 dst_sel:DWORD dst_unused:UNUSED_PAD src0_sel:WORD_1
	v_cvt_f32_f16_sdwa v95, v13 dst_sel:DWORD dst_unused:UNUSED_PAD src0_sel:WORD_1
	v_cvt_f32_f16_e32 v92, v12
	v_cvt_f32_f16_e32 v94, v13
	v_pk_add_f32 v[2:3], v[2:3], v[4:5]
	v_mov_b32_e32 v4, v80
	v_mov_b32_e32 v5, v82
	v_mov_b32_e32 v6, v81
	v_mov_b32_e32 v7, v83
	v_cvt_f32_f16_sdwa v89, v10 dst_sel:DWORD dst_unused:UNUSED_PAD src0_sel:WORD_1
	v_cvt_f32_f16_sdwa v91, v11 dst_sel:DWORD dst_unused:UNUSED_PAD src0_sel:WORD_1
	s_waitcnt vmcnt(4)
	v_cvt_f32_f16_sdwa v101, v15 dst_sel:DWORD dst_unused:UNUSED_PAD src0_sel:WORD_1
	v_cvt_f32_f16_e32 v100, v15
	v_cvt_f32_f16_sdwa v113, v17 dst_sel:DWORD dst_unused:UNUSED_PAD src0_sel:WORD_1
	v_cvt_f32_f16_e32 v112, v17
	v_pk_add_f32 v[4:5], v[4:5], v[6:7]
	v_mov_b32_e32 v6, v84
	v_mov_b32_e32 v7, v86
	v_mov_b32_e32 v8, v85
	v_mov_b32_e32 v9, v87
	v_cvt_f32_f16_e32 v88, v10
	v_cvt_f32_f16_e32 v90, v11
	v_cvt_f32_f16_sdwa v99, v14 dst_sel:DWORD dst_unused:UNUSED_PAD src0_sel:WORD_1
	v_cvt_f32_f16_e32 v98, v14
	v_pk_add_f32 v[6:7], v[6:7], v[8:9]
	v_mov_b32_e32 v12, v93
	v_mov_b32_e32 v96, v95
	v_cvt_f32_f16_sdwa v103, v16 dst_sel:DWORD dst_unused:UNUSED_PAD src0_sel:WORD_1
	v_cvt_f32_f16_e32 v102, v16
	v_pk_add_f32 v[4:5], v[4:5], v[4:5] op_sel:[0,1] op_sel_hi:[1,0]
	v_pk_add_f32 v[6:7], v[6:7], v[6:7] op_sel:[0,1] op_sel_hi:[1,0]
	v_pk_add_f32 v[12:13], v[12:13], v[92:93]
	v_pk_add_f32 v[96:97], v[96:97], v[94:95]
	v_pk_add_f32 v[2:3], v[2:3], v[2:3] op_sel:[0,1] op_sel_hi:[1,0]
	v_mov_b32_e32 v8, v89
	v_mov_b32_e32 v10, v91
	v_mov_b32_e32 v5, v100
	v_mov_b32_e32 v7, v101
	v_mov_b32_e32 v13, v112
	v_mov_b32_e32 v97, v113
	v_pk_add_f32 v[8:9], v[8:9], v[88:89]
	v_pk_add_f32 v[10:11], v[10:11], v[90:91]
	v_mov_b32_e32 v3, v98
	v_mov_b32_e32 v37, v99
	v_pk_add_f32 v[4:5], v[4:5], v[6:7]
	v_pk_add_f32 v[6:7], v[12:13], v[96:97]
	s_waitcnt vmcnt(3)
	v_cvt_f32_f16_sdwa v97, v18 dst_sel:DWORD dst_unused:UNUSED_PAD src0_sel:WORD_1
	v_cvt_f32_f16_e32 v96, v18
	v_cvt_f32_f16_sdwa v147, v20 dst_sel:DWORD dst_unused:UNUSED_PAD src0_sel:WORD_1
	v_cvt_f32_f16_e32 v146, v20
	v_pk_add_f32 v[2:3], v[2:3], v[36:37]
	v_mov_b32_e32 v9, v102
	v_mov_b32_e32 v11, v103
	v_cvt_f32_f16_sdwa v145, v19 dst_sel:DWORD dst_unused:UNUSED_PAD src0_sel:WORD_1
	v_cvt_f32_f16_e32 v144, v19
	v_cvt_f32_f16_sdwa v149, v21 dst_sel:DWORD dst_unused:UNUSED_PAD src0_sel:WORD_1
	v_cvt_f32_f16_e32 v148, v21
	v_pk_add_f32 v[2:3], v[2:3], v[4:5]
	v_pk_add_f32 v[4:5], v[8:9], v[10:11]
	s_waitcnt vmcnt(2)
	v_cvt_f32_f16_e32 v150, v22
	v_pk_add_f32 v[4:5], v[4:5], v[6:7]
	v_cvt_f32_f16_e32 v152, v23
	v_cvt_f32_f16_sdwa v151, v22 dst_sel:DWORD dst_unused:UNUSED_PAD src0_sel:WORD_1
	v_cvt_f32_f16_sdwa v153, v23 dst_sel:DWORD dst_unused:UNUSED_PAD src0_sel:WORD_1
	v_pk_add_f32 v[2:3], v[2:3], v[4:5]
	v_mov_b32_e32 v4, v96
	v_mov_b32_e32 v5, v146
	v_mov_b32_e32 v6, v97
	v_mov_b32_e32 v7, v147
	v_cvt_f32_f16_e32 v154, v24
	v_cvt_f32_f16_e32 v156, v25
	v_cvt_f32_f16_sdwa v155, v24 dst_sel:DWORD dst_unused:UNUSED_PAD src0_sel:WORD_1
	v_cvt_f32_f16_sdwa v157, v25 dst_sel:DWORD dst_unused:UNUSED_PAD src0_sel:WORD_1
	v_pk_add_f32 v[4:5], v[4:5], v[6:7]
	v_mov_b32_e32 v6, v144
	v_mov_b32_e32 v7, v148
	v_mov_b32_e32 v8, v145
	v_mov_b32_e32 v9, v149
	v_pk_add_f32 v[6:7], v[6:7], v[8:9]
	s_waitcnt vmcnt(1)
	v_cvt_f32_f16_sdwa v159, v26 dst_sel:DWORD dst_unused:UNUSED_PAD src0_sel:WORD_1
	v_cvt_f32_f16_sdwa v161, v27 dst_sel:DWORD dst_unused:UNUSED_PAD src0_sel:WORD_1
	v_cvt_f32_f16_sdwa v163, v28 dst_sel:DWORD dst_unused:UNUSED_PAD src0_sel:WORD_1
	v_cvt_f32_f16_sdwa v165, v29 dst_sel:DWORD dst_unused:UNUSED_PAD src0_sel:WORD_1
	v_pk_add_f32 v[4:5], v[4:5], v[6:7]
	v_mov_b32_e32 v6, v150
	v_mov_b32_e32 v7, v152
	v_mov_b32_e32 v8, v151
	v_mov_b32_e32 v9, v153
	v_cvt_f32_f16_e32 v158, v26
	v_cvt_f32_f16_e32 v160, v27
	v_cvt_f32_f16_e32 v162, v28
	v_cvt_f32_f16_e32 v164, v29
	s_waitcnt vmcnt(0)
	v_cvt_f32_f16_sdwa v167, v30 dst_sel:DWORD dst_unused:UNUSED_PAD src0_sel:WORD_1
	v_cvt_f32_f16_e32 v166, v30
	v_cvt_f32_f16_sdwa v169, v31 dst_sel:DWORD dst_unused:UNUSED_PAD src0_sel:WORD_1
	v_cvt_f32_f16_e32 v168, v31
	v_pk_add_f32 v[6:7], v[6:7], v[8:9]
	v_mov_b32_e32 v8, v154
	v_mov_b32_e32 v9, v156
	v_mov_b32_e32 v10, v155
	v_mov_b32_e32 v11, v157
	v_cvt_f32_f16_sdwa v171, v32 dst_sel:DWORD dst_unused:UNUSED_PAD src0_sel:WORD_1
	v_cvt_f32_f16_e32 v170, v32
	v_cvt_f32_f16_sdwa v173, v33 dst_sel:DWORD dst_unused:UNUSED_PAD src0_sel:WORD_1
	v_cvt_f32_f16_e32 v172, v33
	v_pk_add_f32 v[8:9], v[8:9], v[10:11]
	v_pk_add_f32 v[2:3], v[2:3], v[2:3] op_sel:[0,1] op_sel_hi:[1,0]
	v_pk_add_f32 v[4:5], v[4:5], v[4:5] op_sel:[0,1] op_sel_hi:[1,0]
	v_pk_add_f32 v[6:7], v[6:7], v[6:7] op_sel:[0,1] op_sel_hi:[1,0]
	v_pk_add_f32 v[8:9], v[8:9], v[8:9] op_sel:[0,1] op_sel_hi:[1,0]
	v_mov_b32_e32 v10, v159
	v_mov_b32_e32 v12, v161
	v_mov_b32_e32 v14, v163
	v_mov_b32_e32 v16, v165
	v_pk_add_f32 v[10:11], v[10:11], v[158:159]
	v_pk_add_f32 v[12:13], v[12:13], v[160:161]
	v_pk_add_f32 v[14:15], v[14:15], v[162:163]
	v_pk_add_f32 v[16:17], v[16:17], v[164:165]
	v_mov_b32_e32 v3, v166
	v_mov_b32_e32 v5, v167
	v_mov_b32_e32 v7, v168
	v_mov_b32_e32 v9, v169
	v_pk_add_f32 v[2:3], v[2:3], v[4:5]
	v_pk_add_f32 v[4:5], v[6:7], v[8:9]
	v_mov_b32_e32 v11, v170
	v_mov_b32_e32 v13, v171
	v_mov_b32_e32 v15, v172
	v_mov_b32_e32 v17, v173
	v_pk_add_f32 v[2:3], v[2:3], v[4:5]
	v_pk_add_f32 v[4:5], v[10:11], v[12:13]
	v_pk_add_f32 v[6:7], v[14:15], v[16:17]
	s_nop 0
	v_pk_add_f32 v[4:5], v[4:5], v[6:7]
	s_nop 0
	v_pk_add_f32 v[2:3], v[2:3], v[4:5]
	v_mov_b32_e32 v4, v34
	v_add_f32_e32 v2, v2, v3
	ds_bpermute_b32 v3, v105, v2
	v_add_u32_e32 v34, s8, v4
	v_cmp_gt_i32_e32 vcc, s14, v34
	v_cmp_lt_i32_e64 s[0:1], s9, v34
	s_waitcnt lgkmcnt(0)
	v_add_f32_e32 v2, v2, v3
	ds_bpermute_b32 v3, v138, v2
	s_waitcnt lgkmcnt(0)
	v_add_f32_e32 v5, v2, v3
	ds_bpermute_b32 v6, v139, v5
	v_cndmask_b32_e32 v2, v4, v34, vcc
	v_ashrrev_i32_e32 v3, 31, v2
	v_lshlrev_b64 v[2:3], 13, v[2:3]
	v_lshl_add_u64 v[18:19], v[38:39], 0, v[2:3]
	s_waitcnt lgkmcnt(0)
	v_add_f32_e32 v20, v5, v6
	ds_bpermute_b32 v21, v140, v20
	v_add_co_u32_e32 v30, vcc, s15, v18
	global_load_dwordx4 v[2:5], v[18:19], off
	global_load_dwordx4 v[6:9], v[18:19], off offset:1024
	global_load_dwordx4 v[10:13], v[18:19], off offset:2048
	global_load_dwordx4 v[14:17], v[18:19], off offset:3072
	v_addc_co_u32_e32 v31, vcc, 0, v19, vcc
	s_waitcnt lgkmcnt(0)
	v_add_f32_e32 v20, v20, v21
	ds_bpermute_b32 v21, v141, v20
	s_andn2_b64 vcc, exec, s[10:11]
	s_waitcnt lgkmcnt(0)
	v_add_f32_e32 v37, v20, v21
	ds_bpermute_b32 v104, v142, v37
	global_load_dwordx4 v[18:21], v[30:31], off
	global_load_dwordx4 v[22:25], v[30:31], off offset:1024
	global_load_dwordx4 v[26:29], v[30:31], off offset:2048
	s_nop 0
	global_load_dwordx4 v[30:33], v[30:31], off offset:3072
	s_waitcnt lgkmcnt(0)
	v_add_f32_e32 v37, v37, v104
	v_mul_f32_e32 v104, 0x39800000, v37
	v_pk_add_f32 v[130:131], v[72:73], v[104:105] op_sel_hi:[1,0] neg_lo:[0,1] neg_hi:[0,1]
	v_pk_add_f32 v[132:133], v[74:75], v[104:105] op_sel_hi:[1,0] neg_lo:[0,1] neg_hi:[0,1]
	v_pk_mul_f32 v[174:175], v[130:131], v[130:131]
	v_pk_mul_f32 v[176:177], v[132:133], v[132:133]
	v_add_f32_e32 v37, v174, v175
	v_pk_add_f32 v[134:135], v[76:77], v[104:105] op_sel_hi:[1,0] neg_lo:[0,1] neg_hi:[0,1]
	v_add_f32_e32 v37, v176, v37
	v_pk_mul_f32 v[178:179], v[134:135], v[134:135]
	v_add_f32_e32 v37, v177, v37
	v_pk_add_f32 v[136:137], v[78:79], v[104:105] op_sel_hi:[1,0] neg_lo:[0,1] neg_hi:[0,1]
	v_add_f32_e32 v37, v178, v37
	v_pk_mul_f32 v[180:181], v[136:137], v[136:137]
	v_add_f32_e32 v37, v179, v37
	v_pk_add_f32 v[122:123], v[80:81], v[104:105] op_sel_hi:[1,0] neg_lo:[0,1] neg_hi:[0,1]
	v_add_f32_e32 v37, v180, v37
	v_pk_mul_f32 v[182:183], v[122:123], v[122:123]
	v_add_f32_e32 v37, v181, v37
	v_pk_add_f32 v[124:125], v[82:83], v[104:105] op_sel_hi:[1,0] neg_lo:[0,1] neg_hi:[0,1]
	v_add_f32_e32 v37, v182, v37
	v_pk_mul_f32 v[184:185], v[124:125], v[124:125]
	v_add_f32_e32 v37, v183, v37
	v_pk_add_f32 v[126:127], v[84:85], v[104:105] op_sel_hi:[1,0] neg_lo:[0,1] neg_hi:[0,1]
	v_add_f32_e32 v37, v184, v37
	v_pk_mul_f32 v[186:187], v[126:127], v[126:127]
	v_add_f32_e32 v37, v185, v37
	v_pk_add_f32 v[128:129], v[86:87], v[104:105] op_sel_hi:[1,0] neg_lo:[0,1] neg_hi:[0,1]
	v_add_f32_e32 v37, v186, v37
	v_pk_mul_f32 v[188:189], v[128:129], v[128:129]
	v_add_f32_e32 v37, v187, v37
	v_pk_add_f32 v[114:115], v[88:89], v[104:105] op_sel_hi:[1,0] neg_lo:[0,1] neg_hi:[0,1]
	v_add_f32_e32 v37, v188, v37
	v_pk_mul_f32 v[190:191], v[114:115], v[114:115]
	v_add_f32_e32 v37, v189, v37
	v_pk_add_f32 v[116:117], v[90:91], v[104:105] op_sel_hi:[1,0] neg_lo:[0,1] neg_hi:[0,1]
	v_add_f32_e32 v37, v190, v37
	v_pk_mul_f32 v[192:193], v[116:117], v[116:117]
	v_add_f32_e32 v37, v191, v37
	v_pk_add_f32 v[118:119], v[92:93], v[104:105] op_sel_hi:[1,0] neg_lo:[0,1] neg_hi:[0,1]
	v_add_f32_e32 v37, v192, v37
	v_pk_mul_f32 v[194:195], v[118:119], v[118:119]
	v_add_f32_e32 v37, v193, v37
	v_pk_add_f32 v[120:121], v[94:95], v[104:105] op_sel_hi:[1,0] neg_lo:[0,1] neg_hi:[0,1]
	v_add_f32_e32 v37, v194, v37
	v_pk_mul_f32 v[196:197], v[120:121], v[120:121]
	v_add_f32_e32 v37, v195, v37
	v_pk_add_f32 v[106:107], v[98:99], v[104:105] op_sel_hi:[1,0] neg_lo:[0,1] neg_hi:[0,1]
	v_add_f32_e32 v37, v196, v37
	v_pk_mul_f32 v[198:199], v[106:107], v[106:107]
	v_add_f32_e32 v37, v197, v37
	v_pk_add_f32 v[108:109], v[100:101], v[104:105] op_sel_hi:[1,0] neg_lo:[0,1] neg_hi:[0,1]
	v_add_f32_e32 v37, v198, v37
	v_pk_mul_f32 v[200:201], v[108:109], v[108:109]
	v_add_f32_e32 v37, v199, v37
	v_pk_add_f32 v[110:111], v[102:103], v[104:105] op_sel_hi:[1,0] neg_lo:[0,1] neg_hi:[0,1]
	v_add_f32_e32 v37, v200, v37
	v_pk_mul_f32 v[202:203], v[110:111], v[110:111]
	v_add_f32_e32 v37, v201, v37
	v_pk_add_f32 v[112:113], v[112:113], v[104:105] op_sel_hi:[1,0] neg_lo:[0,1] neg_hi:[0,1]
	v_add_f32_e32 v37, v202, v37
	v_pk_mul_f32 v[204:205], v[112:113], v[112:113]
	v_add_f32_e32 v37, v203, v37
	v_pk_add_f32 v[96:97], v[96:97], v[104:105] op_sel_hi:[1,0] neg_lo:[0,1] neg_hi:[0,1]
	v_add_f32_e32 v37, v204, v37
	v_pk_mul_f32 v[206:207], v[96:97], v[96:97]
	v_add_f32_e32 v37, v205, v37
	v_pk_add_f32 v[98:99], v[144:145], v[104:105] op_sel_hi:[1,0] neg_lo:[0,1] neg_hi:[0,1]
	v_add_f32_e32 v37, v206, v37
	v_pk_mul_f32 v[144:145], v[98:99], v[98:99]
	v_add_f32_e32 v37, v207, v37
	v_pk_add_f32 v[100:101], v[146:147], v[104:105] op_sel_hi:[1,0] neg_lo:[0,1] neg_hi:[0,1]
	v_add_f32_e32 v37, v144, v37
	v_pk_mul_f32 v[146:147], v[100:101], v[100:101]
	v_add_f32_e32 v37, v145, v37
	v_pk_add_f32 v[102:103], v[148:149], v[104:105] op_sel_hi:[1,0] neg_lo:[0,1] neg_hi:[0,1]
	v_add_f32_e32 v37, v146, v37
	v_pk_mul_f32 v[148:149], v[102:103], v[102:103]
	v_add_f32_e32 v37, v147, v37
	v_pk_add_f32 v[88:89], v[150:151], v[104:105] op_sel_hi:[1,0] neg_lo:[0,1] neg_hi:[0,1]
	v_add_f32_e32 v37, v148, v37
	v_pk_mul_f32 v[150:151], v[88:89], v[88:89]
	v_add_f32_e32 v37, v149, v37
	v_pk_add_f32 v[90:91], v[152:153], v[104:105] op_sel_hi:[1,0] neg_lo:[0,1] neg_hi:[0,1]
	v_add_f32_e32 v37, v150, v37
	v_pk_mul_f32 v[152:153], v[90:91], v[90:91]
	v_add_f32_e32 v37, v151, v37
	v_pk_add_f32 v[92:93], v[154:155], v[104:105] op_sel_hi:[1,0] neg_lo:[0,1] neg_hi:[0,1]
	v_add_f32_e32 v37, v152, v37
	v_pk_mul_f32 v[154:155], v[92:93], v[92:93]
	v_add_f32_e32 v37, v153, v37
	v_pk_add_f32 v[94:95], v[156:157], v[104:105] op_sel_hi:[1,0] neg_lo:[0,1] neg_hi:[0,1]
	v_add_f32_e32 v37, v154, v37
	v_pk_mul_f32 v[156:157], v[94:95], v[94:95]
	v_add_f32_e32 v37, v155, v37
	v_pk_add_f32 v[80:81], v[158:159], v[104:105] op_sel_hi:[1,0] neg_lo:[0,1] neg_hi:[0,1]
	v_add_f32_e32 v37, v156, v37
	v_pk_mul_f32 v[158:159], v[80:81], v[80:81]
	v_add_f32_e32 v37, v157, v37
	v_pk_add_f32 v[82:83], v[160:161], v[104:105] op_sel_hi:[1,0] neg_lo:[0,1] neg_hi:[0,1]
	v_add_f32_e32 v37, v158, v37
	v_pk_mul_f32 v[160:161], v[82:83], v[82:83]
	v_add_f32_e32 v37, v159, v37
	v_pk_add_f32 v[84:85], v[162:163], v[104:105] op_sel_hi:[1,0] neg_lo:[0,1] neg_hi:[0,1]
	v_add_f32_e32 v37, v160, v37
	v_pk_mul_f32 v[162:163], v[84:85], v[84:85]
	v_add_f32_e32 v37, v161, v37
	v_pk_add_f32 v[86:87], v[164:165], v[104:105] op_sel_hi:[1,0] neg_lo:[0,1] neg_hi:[0,1]
	v_add_f32_e32 v37, v162, v37
	v_pk_mul_f32 v[164:165], v[86:87], v[86:87]
	v_add_f32_e32 v37, v163, v37
	v_pk_add_f32 v[72:73], v[166:167], v[104:105] op_sel_hi:[1,0] neg_lo:[0,1] neg_hi:[0,1]
	v_add_f32_e32 v37, v164, v37
	v_pk_mul_f32 v[166:167], v[72:73], v[72:73]
	v_add_f32_e32 v37, v165, v37
	v_pk_add_f32 v[74:75], v[168:169], v[104:105] op_sel_hi:[1,0] neg_lo:[0,1] neg_hi:[0,1]
	v_add_f32_e32 v37, v166, v37
	v_pk_mul_f32 v[168:169], v[74:75], v[74:75]
	v_add_f32_e32 v37, v167, v37
	v_pk_add_f32 v[76:77], v[170:171], v[104:105] op_sel_hi:[1,0] neg_lo:[0,1] neg_hi:[0,1]
	v_add_f32_e32 v37, v168, v37
	v_pk_mul_f32 v[170:171], v[76:77], v[76:77]
	v_add_f32_e32 v37, v169, v37
	v_pk_add_f32 v[78:79], v[172:173], v[104:105] op_sel_hi:[1,0] neg_lo:[0,1] neg_hi:[0,1]
	v_add_f32_e32 v37, v170, v37
	v_pk_mul_f32 v[172:173], v[78:79], v[78:79]
	v_add_f32_e32 v37, v171, v37
	v_add_f32_e32 v37, v172, v37
	v_add_f32_e32 v37, v173, v37
	ds_bpermute_b32 v104, v105, v37
	s_waitcnt lgkmcnt(0)
	v_add_f32_e32 v37, v37, v104
	ds_bpermute_b32 v104, v138, v37
	s_waitcnt lgkmcnt(0)
	v_add_f32_e32 v37, v37, v104
	ds_bpermute_b32 v104, v139, v37
	s_waitcnt lgkmcnt(0)
	v_add_f32_e32 v37, v37, v104
	ds_bpermute_b32 v104, v140, v37
	s_waitcnt lgkmcnt(0)
	v_add_f32_e32 v37, v37, v104
	ds_bpermute_b32 v104, v141, v37
	s_waitcnt lgkmcnt(0)
	v_add_f32_e32 v37, v37, v104
	ds_bpermute_b32 v104, v142, v37
	s_cbranch_vccnz .LBB0_2433
	ds_read_b128 v[144:147], v251 offset:16
	ds_read_b128 v[148:151], v251 offset:16400
	ds_read_b128 v[152:155], v251 offset:16384
	ds_read_b128 v[156:159], v251 offset:0
	s_waitcnt lgkmcnt(0)
	v_add_f32_e32 v37, v37, v104
	v_fmamk_f32 v37, v37, 0x39800000, v35
	v_mul_f32_e32 v104, 0x4b800000, v37
	v_cmp_gt_f32_e32 vcc, s18, v37
	s_nop 1
	v_cndmask_b32_e32 v37, v37, v104, vcc
	v_rsq_f32_e32 v37, v37
	s_nop 0
	v_mul_f32_e32 v104, 0x45800000, v37
	v_cndmask_b32_e32 v104, v37, v104, vcc
	v_pk_mul_f32 v[134:135], v[134:135], v[104:105] op_sel_hi:[1,0]
	v_pk_mul_f32 v[136:137], v[136:137], v[104:105] op_sel_hi:[1,0]
	v_pk_mul_f32 v[160:161], v[130:131], v[104:105] op_sel_hi:[1,0]
	v_pk_mul_f32 v[162:163], v[132:133], v[104:105] op_sel_hi:[1,0]
	v_pk_mul_f32 v[128:129], v[128:129], v[104:105] op_sel_hi:[1,0]
	v_pk_mul_f32 v[126:127], v[126:127], v[104:105] op_sel_hi:[1,0]
	v_pk_mul_f32 v[120:121], v[120:121], v[104:105] op_sel_hi:[1,0]
	v_pk_mul_f32 v[118:119], v[118:119], v[104:105] op_sel_hi:[1,0]
	v_pk_mul_f32 v[112:113], v[112:113], v[104:105] op_sel_hi:[1,0]
	v_pk_mul_f32 v[110:111], v[110:111], v[104:105] op_sel_hi:[1,0]
	v_pk_mul_f32 v[102:103], v[102:103], v[104:105] op_sel_hi:[1,0]
	v_pk_mul_f32 v[100:101], v[100:101], v[104:105] op_sel_hi:[1,0]
	v_pk_mul_f32 v[94:95], v[94:95], v[104:105] op_sel_hi:[1,0]
	v_pk_mul_f32 v[92:93], v[92:93], v[104:105] op_sel_hi:[1,0]
	v_pk_mul_f32 v[86:87], v[86:87], v[104:105] op_sel_hi:[1,0]
	v_pk_mul_f32 v[84:85], v[84:85], v[104:105] op_sel_hi:[1,0]
	v_pk_mul_f32 v[78:79], v[78:79], v[104:105] op_sel_hi:[1,0]
	v_pk_mul_f32 v[76:77], v[76:77], v[104:105] op_sel_hi:[1,0]
	s_waitcnt lgkmcnt(2)
	v_pk_fma_f32 v[132:133], v[136:137], v[146:147], v[150:151]
	v_pk_fma_f32 v[130:131], v[134:135], v[144:145], v[148:149]
	s_waitcnt lgkmcnt(0)
	v_pk_fma_f32 v[136:137], v[162:163], v[158:159], v[154:155]
	v_pk_fma_f32 v[134:135], v[160:161], v[156:157], v[152:153]
	global_store_dwordx4 v[0:1], v[134:137], off
	global_store_dwordx4 v[0:1], v[130:133], off offset:16
	ds_read_b128 v[130:133], v251 offset:2064
	s_nop 0
	ds_read_b128 v[134:137], v251 offset:18448
	ds_read_b128 v[144:147], v251 offset:18432
	ds_read_b128 v[148:151], v251 offset:2048
	v_pk_mul_f32 v[152:153], v[124:125], v[104:105] op_sel_hi:[1,0]
	v_pk_mul_f32 v[154:155], v[122:123], v[104:105] op_sel_hi:[1,0]
	s_waitcnt lgkmcnt(2)
	v_pk_fma_f32 v[122:123], v[126:127], v[130:131], v[134:135]
	v_pk_fma_f32 v[124:125], v[128:129], v[132:133], v[136:137]
	s_waitcnt lgkmcnt(0)
	v_pk_fma_f32 v[126:127], v[154:155], v[148:149], v[144:145]
	v_pk_fma_f32 v[128:129], v[152:153], v[150:151], v[146:147]
	global_store_dwordx4 v[0:1], v[126:129], off offset:2048
	global_store_dwordx4 v[0:1], v[122:125], off offset:2064
	ds_read_b128 v[122:125], v251 offset:4112
	s_nop 0
	ds_read_b128 v[126:129], v251 offset:20496
	ds_read_b128 v[130:133], v251 offset:20480
	ds_read_b128 v[134:137], v251 offset:4096
	v_add_co_u32_e32 v144, vcc, s15, v0
	v_pk_mul_f32 v[148:149], v[116:117], v[104:105] op_sel_hi:[1,0]
	s_nop 0
	v_addc_co_u32_e32 v145, vcc, 0, v1, vcc
	v_add_co_u32_e32 v146, vcc, s16, v0
	v_pk_mul_f32 v[150:151], v[114:115], v[104:105] op_sel_hi:[1,0]
	s_nop 0
	v_addc_co_u32_e32 v147, vcc, 0, v1, vcc
	s_waitcnt lgkmcnt(2)
	v_pk_fma_f32 v[114:115], v[118:119], v[122:123], v[126:127]
	v_pk_fma_f32 v[116:117], v[120:121], v[124:125], v[128:129]
	s_waitcnt lgkmcnt(0)
	v_pk_fma_f32 v[118:119], v[150:151], v[134:135], v[130:131]
	v_pk_fma_f32 v[120:121], v[148:149], v[136:137], v[132:133]
	global_store_dwordx4 v[146:147], v[118:121], off offset:-4096
	global_store_dwordx4 v[144:145], v[114:117], off offset:16
	ds_read_b128 v[114:117], v251 offset:6160
	s_nop 0
	ds_read_b128 v[118:121], v251 offset:22544
	ds_read_b128 v[122:125], v251 offset:22528
	ds_read_b128 v[126:129], v251 offset:6144
	v_pk_mul_f32 v[130:131], v[108:109], v[104:105] op_sel_hi:[1,0]
	v_pk_mul_f32 v[132:133], v[106:107], v[104:105] op_sel_hi:[1,0]
	s_waitcnt lgkmcnt(2)
	v_pk_fma_f32 v[106:107], v[110:111], v[114:115], v[118:119]
	v_pk_fma_f32 v[108:109], v[112:113], v[116:117], v[120:121]
	s_waitcnt lgkmcnt(0)
	v_pk_fma_f32 v[110:111], v[132:133], v[126:127], v[122:123]
	v_pk_fma_f32 v[112:113], v[130:131], v[128:129], v[124:125]
	global_store_dwordx4 v[144:145], v[110:113], off offset:2048
	global_store_dwordx4 v[144:145], v[106:109], off offset:2064
	ds_read_b128 v[106:109], v251 offset:8208
	s_nop 0
	ds_read_b128 v[110:113], v251 offset:24592
	ds_read_b128 v[114:117], v251 offset:24576
	ds_read_b128 v[118:121], v251 offset:8192
	v_pk_mul_f32 v[122:123], v[98:99], v[104:105] op_sel_hi:[1,0]
	v_pk_mul_f32 v[124:125], v[96:97], v[104:105] op_sel_hi:[1,0]
	s_waitcnt lgkmcnt(2)
	v_pk_fma_f32 v[96:97], v[100:101], v[106:107], v[110:111]
	v_pk_fma_f32 v[98:99], v[102:103], v[108:109], v[112:113]
	s_waitcnt lgkmcnt(0)
	v_pk_fma_f32 v[100:101], v[124:125], v[118:119], v[114:115]
	v_pk_fma_f32 v[102:103], v[122:123], v[120:121], v[116:117]
	global_store_dwordx4 v[146:147], v[100:103], off
	global_store_dwordx4 v[146:147], v[96:99], off offset:16
	ds_read_b128 v[96:99], v251 offset:10256
	s_nop 0
	ds_read_b128 v[100:103], v251 offset:26640
	ds_read_b128 v[106:109], v251 offset:26624
	ds_read_b128 v[110:113], v251 offset:10240
	v_pk_mul_f32 v[114:115], v[90:91], v[104:105] op_sel_hi:[1,0]
	v_pk_mul_f32 v[116:117], v[88:89], v[104:105] op_sel_hi:[1,0]
	s_waitcnt lgkmcnt(2)
	v_pk_fma_f32 v[88:89], v[92:93], v[96:97], v[100:101]
	v_pk_fma_f32 v[90:91], v[94:95], v[98:99], v[102:103]
	s_waitcnt lgkmcnt(0)
	v_pk_fma_f32 v[92:93], v[116:117], v[110:111], v[106:107]
	v_pk_fma_f32 v[94:95], v[114:115], v[112:113], v[108:109]
	global_store_dwordx4 v[146:147], v[92:95], off offset:2048
	global_store_dwordx4 v[146:147], v[88:91], off offset:2064
	ds_read_b128 v[88:91], v251 offset:12304
	s_nop 0
	ds_read_b128 v[92:95], v251 offset:28688
	ds_read_b128 v[96:99], v251 offset:28672
	ds_read_b128 v[100:103], v251 offset:12288
	v_add_co_u32_e32 v106, vcc, s17, v0
	v_pk_mul_f32 v[108:109], v[82:83], v[104:105] op_sel_hi:[1,0]
	v_pk_mul_f32 v[110:111], v[80:81], v[104:105] op_sel_hi:[1,0]
	v_addc_co_u32_e32 v107, vcc, 0, v1, vcc
	s_waitcnt lgkmcnt(2)
	v_pk_fma_f32 v[80:81], v[84:85], v[88:89], v[92:93]
	v_pk_fma_f32 v[82:83], v[86:87], v[90:91], v[94:95]
	s_waitcnt lgkmcnt(0)
	v_pk_fma_f32 v[84:85], v[110:111], v[100:101], v[96:97]
	v_pk_fma_f32 v[86:87], v[108:109], v[102:103], v[98:99]
	global_store_dwordx4 v[106:107], v[84:87], off
	global_store_dwordx4 v[106:107], v[80:83], off offset:16
	ds_read_b128 v[80:83], v251 offset:14352
	s_nop 0
	ds_read_b128 v[84:87], v251 offset:30736
	ds_read_b128 v[88:91], v251 offset:30720
	ds_read_b128 v[92:95], v251 offset:14336
	v_pk_mul_f32 v[96:97], v[74:75], v[104:105] op_sel_hi:[1,0]
	v_pk_mul_f32 v[98:99], v[72:73], v[104:105] op_sel_hi:[1,0]
	s_waitcnt lgkmcnt(2)
	v_pk_fma_f32 v[72:73], v[76:77], v[80:81], v[84:85]
	v_pk_fma_f32 v[74:75], v[78:79], v[82:83], v[86:87]
	s_waitcnt lgkmcnt(0)
	v_pk_fma_f32 v[76:77], v[98:99], v[92:93], v[88:89]
	v_pk_fma_f32 v[78:79], v[96:97], v[94:95], v[90:91]
	global_store_dwordx4 v[106:107], v[76:79], off offset:2048
	global_store_dwordx4 v[106:107], v[72:75], off offset:2064
	s_branch .LBB0_2433
